# pass1 rewritten: one workgroup barrier per chunk (double/quad-buffered LDS tiles, raw rows two chunks ahead), transposed 8-byte prepare, waves 0-3 prepare->update and 4-7 update->prepare; on top of pa
# speedup vs baseline: 1.0009x; 1.0009x over previous
.LBB0_1150:
	s_ashr_i32 s0, s2, 6
	s_ashr_i32 s1, s0, 31
	s_lshl_b32 s3, s2, 8
	s_lshl_b64 s[0:1], s[0:1], 12
	s_and_b32 s3, s3, 0xf00
	s_or_b32 s4, s0, s3
	s_mov_b32 s5, s1
	v_lshl_add_u64 v[8:9], s[4:5], 0, v[54:55]
	v_mov_b64_e32 v[10:11], s[52:53]
	s_movk_i32 s6, 0x1600
	v_mad_u64_u32 v[10:11], s[4:5], v8, s6, v[10:11]
	s_lshl_b32 s3, s2, 4
	v_mad_i32_i24 v11, v9, s6, v11
	s_and_b32 s54, s3, 0x300
	v_lshl_add_u64 v[8:9], v[10:11], 0, s[54:55]
	v_mov_b32_e32 v61, v16
	v_lshl_add_u64 v[8:9], v[8:9], 0, v[60:61]
	global_load_dwordx4 v[42:45], v[8:9], off offset:2560
	global_load_dwordx4 v[46:49], v[8:9], off offset:3584
	s_lshl_b32 s4, s8, 1
	s_and_b32 s4, s4, 0x300
	v_mov_b32_e32 v8, s4
	v_readfirstlane_b32 s4, v17
	s_ashr_i32 s5, s4, 6
	s_lshl_b32 s4, s5, 4
	v_or_b32_e32 v10, s4, v64
	s_and_b32 s3, s9, 0xf00
	v_lshlrev_b32_e32 v12, 1, v10
	v_or_b32_e32 v10, s4, v56
	v_lshlrev_b32_e32 v74, 1, v10
	v_or_b32_e32 v10, s4, v67
	s_or_b32 s0, s0, s3
	v_mov_b32_e32 v9, v16
	v_lshlrev_b32_e32 v13, 1, v10
	v_lshl_add_u64 v[10:11], s[0:1], 0, v[54:55]
	v_mad_u64_u32 v[8:9], s[0:1], v10, s6, v[8:9]
	v_mad_i32_i24 v9, v11, s6, v9
	v_mov_b32_e32 v61, 0
	v_add_u32_e32 v76, 0, v74
	v_lshl_add_u64 v[62:63], v[58:59], 0, v[8:9]
	s_mov_b64 s[6:7], 0
	v_add_u32_e32 v78, v65, v12
	v_add_u32_e32 v73, v66, v13
	v_mov_b32_e32 v8, 0
	v_mov_b32_e32 v9, v61
	v_mov_b32_e32 v10, v61
	v_mov_b32_e32 v11, v61
	v_mov_b32_e32 v12, 0
	v_mov_b32_e32 v13, v61
	v_mov_b32_e32 v14, v61
	v_mov_b32_e32 v15, v61
	v_mov_b32_e32 v18, 0
	v_mov_b32_e32 v19, v61
	v_mov_b32_e32 v20, v61
	v_mov_b32_e32 v21, v61
	v_mov_b32_e32 v22, 0
	v_mov_b32_e32 v23, v61
	v_mov_b32_e32 v24, v61
	v_mov_b32_e32 v25, v61
	v_mov_b32_e32 v26, 0
	v_mov_b32_e32 v27, v61
	v_mov_b32_e32 v28, v61
	v_mov_b32_e32 v29, v61
	v_mov_b32_e32 v30, 0
	v_mov_b32_e32 v31, v61
	v_mov_b32_e32 v32, v61
	v_mov_b32_e32 v33, v61
	v_mov_b32_e32 v34, 0
	v_mov_b32_e32 v35, v61
	v_mov_b32_e32 v36, v61
	v_mov_b32_e32 v37, v61
	v_mov_b32_e32 v38, 0
	v_mov_b32_e32 v39, v61
	v_mov_b32_e32 v40, v61
	v_mov_b32_e32 v41, v61
	v_add_u32_e32 v77, v76, v69
	v_bfe_u32 v204, v17, 4, 2
	v_lshlrev_b32_e32 v204, 3, v204
	v_lshl_or_b32 v204, s4, 1, v204
	v_mul_u32_u24_e32 v205, 0x140, v56
	v_add_u32_e32 v205, v205, v204
	v_lshlrev_b32_e32 v206, 1, v204
	v_mov_b32_e32 v208, 0
	v_mov_b32_e32 v209, 0
	v_mov_b32_e32 v210, 0
	v_mov_b32_e32 v211, 0
	s_mov_b32 s0, 0x6b2c000
	v_add_co_u32_e64 v196, s[0:1], s0, v62
	s_nop 1
	v_addc_co_u32_e64 v197, s[0:1], 0, v63, s[0:1]
	global_load_dwordx4 v[200:203], v[196:197], off offset:3584
	global_load_dwordx4 v[196:199], v[196:197], off offset:2560
	s_waitcnt vmcnt(3)
	ds_write_b128 v70, v[42:45] offset:17408
	s_waitcnt vmcnt(2)
	ds_write_b128 v70, v[46:49] offset:37888
	s_mov_b32 s0, 0x6b58000
	v_add_co_u32_e64 v42, s[0:1], s0, v62
	s_nop 1
	v_addc_co_u32_e64 v43, s[0:1], 0, v63, s[0:1]
	global_load_dwordx4 v[46:49], v[42:43], off offset:3584
	global_load_dwordx4 v[42:45], v[42:43], off offset:2560
	s_waitcnt lgkmcnt(0)
	s_barrier
	ds_read_b64_tr_b16 v[80:81], v78 offset:17408
	ds_read_b64_tr_b16 v[82:83], v78 offset:18688
	ds_read_b64 v[92:93], v205 offset:17408
	ds_read_b64 v[94:95], v205 offset:22528
	s_waitcnt lgkmcnt(2)
	v_mfma_f32_16x16x32_bf16 v[84:87], v[80:83], v[4:7], 0
	v_mfma_f32_16x16x32_bf16 v[88:91], v[80:83], v[0:3], 0
	s_waitcnt lgkmcnt(0)
	v_lshlrev_b32_e32 v96, 16, v92
	v_and_b32_e32 v97, 0xffff0000, v92
	v_lshlrev_b32_e32 v98, 16, v93
	v_and_b32_e32 v99, 0xffff0000, v93
	v_lshlrev_b32_e32 v100, 16, v94
	v_and_b32_e32 v101, 0xffff0000, v94
	v_lshlrev_b32_e32 v102, 16, v95
	v_and_b32_e32 v103, 0xffff0000, v95
	v_exp_f32_e32 v96, v96
	v_exp_f32_e32 v97, v97
	v_exp_f32_e32 v98, v98
	v_exp_f32_e32 v99, v99
	v_exp_f32_e32 v100, v100
	v_exp_f32_e32 v101, v101
	v_exp_f32_e32 v102, v102
	v_exp_f32_e32 v103, v103
	v_sub_f32_e32 v96, 1.0, v96
	v_sub_f32_e32 v97, 1.0, v97
	v_sub_f32_e32 v98, 1.0, v98
	v_sub_f32_e32 v99, 1.0, v99
	v_sub_f32_e32 v100, 1.0, v100
	v_sub_f32_e32 v101, 1.0, v101
	v_sub_f32_e32 v102, 1.0, v102
	v_sub_f32_e32 v103, 1.0, v103
	v_sub_f32_dpp v104, v88, v84 row_newbcast:15 row_mask:0xf bank_mask:0xf
	v_sub_f32_dpp v105, v89, v85 row_newbcast:15 row_mask:0xf bank_mask:0xf
	v_sub_f32_dpp v106, v90, v86 row_newbcast:15 row_mask:0xf bank_mask:0xf
	v_sub_f32_dpp v107, v91, v87 row_newbcast:15 row_mask:0xf bank_mask:0xf
	v_sub_f32_dpp v108, v88, v88 row_newbcast:15 row_mask:0xf bank_mask:0xf
	v_sub_f32_dpp v109, v89, v89 row_newbcast:15 row_mask:0xf bank_mask:0xf
	v_sub_f32_dpp v110, v90, v90 row_newbcast:15 row_mask:0xf bank_mask:0xf
	v_sub_f32_dpp v111, v91, v91 row_newbcast:15 row_mask:0xf bank_mask:0xf
	v_add_f32_dpp v208, v88, v208 row_newbcast:15 row_mask:0xf bank_mask:0xf
	v_add_f32_dpp v209, v89, v209 row_newbcast:15 row_mask:0xf bank_mask:0xf
	v_add_f32_dpp v210, v90, v210 row_newbcast:15 row_mask:0xf bank_mask:0xf
	v_add_f32_dpp v211, v91, v211 row_newbcast:15 row_mask:0xf bank_mask:0xf
	v_exp_f32_dpp v116, v88 row_newbcast:15 row_mask:0xf bank_mask:0xf
	v_exp_f32_dpp v117, v89 row_newbcast:15 row_mask:0xf bank_mask:0xf
	v_exp_f32_dpp v118, v90 row_newbcast:15 row_mask:0xf bank_mask:0xf
	v_exp_f32_dpp v119, v91 row_newbcast:15 row_mask:0xf bank_mask:0xf
	v_exp_f32_e32 v104, v104
	v_exp_f32_e32 v105, v105
	v_exp_f32_e32 v106, v106
	v_exp_f32_e32 v107, v107
	v_exp_f32_e32 v108, v108
	v_exp_f32_e32 v109, v109
	v_exp_f32_e32 v110, v110
	v_exp_f32_e32 v111, v111
	v_mul_f32_e32 v104, v104, v96
	v_mul_f32_e32 v105, v105, v97
	v_mul_f32_e32 v106, v106, v98
	v_mul_f32_e32 v107, v107, v99
	v_mul_f32_e32 v108, v108, v100
	v_mul_f32_e32 v109, v109, v101
	v_mul_f32_e32 v110, v110, v102
	v_mul_f32_e32 v111, v111, v103
	v_cvt_pk_bf16_f32 v112, v104, v105
	v_cvt_pk_bf16_f32 v113, v106, v107
	v_cvt_pk_bf16_f32 v114, v108, v109
	v_cvt_pk_bf16_f32 v115, v110, v111
	ds_write_b64 v205, v[112:113] offset:27648
	ds_write_b64 v205, v[114:115] offset:32768
	ds_write_b128 v206, v[116:119] offset:56832
	s_mov_b32 s7, 0xe400
	v_add_u32_e32 v187, s7, v70
	s_waitcnt vmcnt(3)
	ds_write_b128 v187, v[200:203] offset:37888
	s_waitcnt vmcnt(2)
	ds_write_b128 v187, v[196:199] offset:17408
	s_mov_b32 s0, 0x6b84000
	v_add_co_u32_e64 v196, s[0:1], s0, v62
	s_nop 1
	v_addc_co_u32_e64 v197, s[0:1], 0, v63, s[0:1]
	global_load_dwordx4 v[200:203], v[196:197], off offset:3584
	global_load_dwordx4 v[196:199], v[196:197], off offset:2560
	s_waitcnt lgkmcnt(0)
	s_barrier
	s_mov_b32 s6, 0
.Lp1n_loop:
	s_and_b32 s7, s6, 1
	s_mul_i32 s7, s7, 0xe400
	s_sub_i32 s3, 0xe400, s7
	s_bitcmp1_b32 s6, 1
	s_cselect_b32 s0, 0, 0x9400
	s_sub_i32 s1, 0x9400, s0
	s_add_i32 s0, s0, s7
	s_add_i32 s1, s1, s7
	v_add_u32_e32 v180, s7, v71
	v_add_u32_e32 v181, s7, v68
	v_add_u32_e32 v183, s0, v73
	v_add_u32_e32 v184, s3, v78
	v_add_u32_e32 v185, s3, v205
	v_add_u32_e32 v186, s3, v206
	v_add_u32_e32 v187, s7, v70
	v_add_u32_e32 v188, s1, v70
	s_cmp_ge_u32 s5, 4
	s_cbranch_scc1 .Lp1n_S
.Lp1n_P:
	ds_read_b64_tr_b16 v[80:81], v184 offset:17408
	ds_read_b64_tr_b16 v[82:83], v184 offset:18688
	ds_read_b64 v[92:93], v185 offset:17408
	ds_read_b64 v[94:95], v185 offset:22528
	s_waitcnt lgkmcnt(2)
	v_mfma_f32_16x16x32_bf16 v[84:87], v[80:83], v[4:7], 0
	v_mfma_f32_16x16x32_bf16 v[88:91], v[80:83], v[0:3], 0
	s_waitcnt lgkmcnt(0)
	v_lshlrev_b32_e32 v96, 16, v92
	v_and_b32_e32 v97, 0xffff0000, v92
	v_lshlrev_b32_e32 v98, 16, v93
	v_and_b32_e32 v99, 0xffff0000, v93
	v_lshlrev_b32_e32 v100, 16, v94
	v_and_b32_e32 v101, 0xffff0000, v94
	v_lshlrev_b32_e32 v102, 16, v95
	v_and_b32_e32 v103, 0xffff0000, v95
	v_exp_f32_e32 v96, v96
	v_exp_f32_e32 v97, v97
	v_exp_f32_e32 v98, v98
	v_exp_f32_e32 v99, v99
	v_exp_f32_e32 v100, v100
	v_exp_f32_e32 v101, v101
	v_exp_f32_e32 v102, v102
	v_exp_f32_e32 v103, v103
	v_sub_f32_e32 v96, 1.0, v96
	v_sub_f32_e32 v97, 1.0, v97
	v_sub_f32_e32 v98, 1.0, v98
	v_sub_f32_e32 v99, 1.0, v99
	v_sub_f32_e32 v100, 1.0, v100
	v_sub_f32_e32 v101, 1.0, v101
	v_sub_f32_e32 v102, 1.0, v102
	v_sub_f32_e32 v103, 1.0, v103
	v_sub_f32_dpp v104, v88, v84 row_newbcast:15 row_mask:0xf bank_mask:0xf
	v_sub_f32_dpp v105, v89, v85 row_newbcast:15 row_mask:0xf bank_mask:0xf
	v_sub_f32_dpp v106, v90, v86 row_newbcast:15 row_mask:0xf bank_mask:0xf
	v_sub_f32_dpp v107, v91, v87 row_newbcast:15 row_mask:0xf bank_mask:0xf
	v_sub_f32_dpp v108, v88, v88 row_newbcast:15 row_mask:0xf bank_mask:0xf
	v_sub_f32_dpp v109, v89, v89 row_newbcast:15 row_mask:0xf bank_mask:0xf
	v_sub_f32_dpp v110, v90, v90 row_newbcast:15 row_mask:0xf bank_mask:0xf
	v_sub_f32_dpp v111, v91, v91 row_newbcast:15 row_mask:0xf bank_mask:0xf
	v_add_f32_dpp v208, v88, v208 row_newbcast:15 row_mask:0xf bank_mask:0xf
	v_add_f32_dpp v209, v89, v209 row_newbcast:15 row_mask:0xf bank_mask:0xf
	v_add_f32_dpp v210, v90, v210 row_newbcast:15 row_mask:0xf bank_mask:0xf
	v_add_f32_dpp v211, v91, v211 row_newbcast:15 row_mask:0xf bank_mask:0xf
	v_exp_f32_dpp v116, v88 row_newbcast:15 row_mask:0xf bank_mask:0xf
	v_exp_f32_dpp v117, v89 row_newbcast:15 row_mask:0xf bank_mask:0xf
	v_exp_f32_dpp v118, v90 row_newbcast:15 row_mask:0xf bank_mask:0xf
	v_exp_f32_dpp v119, v91 row_newbcast:15 row_mask:0xf bank_mask:0xf
	v_exp_f32_e32 v104, v104
	v_exp_f32_e32 v105, v105
	v_exp_f32_e32 v106, v106
	v_exp_f32_e32 v107, v107
	v_exp_f32_e32 v108, v108
	v_exp_f32_e32 v109, v109
	v_exp_f32_e32 v110, v110
	v_exp_f32_e32 v111, v111
	v_mul_f32_e32 v104, v104, v96
	v_mul_f32_e32 v105, v105, v97
	v_mul_f32_e32 v106, v106, v98
	v_mul_f32_e32 v107, v107, v99
	v_mul_f32_e32 v108, v108, v100
	v_mul_f32_e32 v109, v109, v101
	v_mul_f32_e32 v110, v110, v102
	v_mul_f32_e32 v111, v111, v103
	v_cvt_pk_bf16_f32 v112, v104, v105
	v_cvt_pk_bf16_f32 v113, v106, v107
	v_cvt_pk_bf16_f32 v114, v108, v109
	v_cvt_pk_bf16_f32 v115, v110, v111
	ds_write_b64 v185, v[112:113] offset:27648
	ds_write_b64 v185, v[114:115] offset:32768
	ds_write_b128 v186, v[116:119] offset:56832
	s_cmp_ge_u32 s5, 4
	s_cbranch_scc1 .Lp1n_R
.Lp1n_S:
	ds_read_b64_tr_b16 v[50:51], v183
	ds_read_b64_tr_b16 v[52:53], v183 offset:5120
	ds_read_b128 v[120:123], v181 offset:56832
	ds_read_b64_tr_b16 v[128:129], v180 offset:27648
	ds_read_b64_tr_b16 v[130:131], v180 offset:32768
	ds_read_b128 v[124:127], v181 offset:56896
	ds_read_b64_tr_b16 v[132:133], v180 offset:27680
	ds_read_b64_tr_b16 v[134:135], v180 offset:32800
	ds_read_b128 v[144:147], v181 offset:56960
	ds_read_b64_tr_b16 v[136:137], v180 offset:27712
	ds_read_b64_tr_b16 v[138:139], v180 offset:32832
	s_waitcnt lgkmcnt(6)
	v_pk_mul_f32 v[38:39], v[38:39], v[120:121]
	v_pk_mul_f32 v[40:41], v[40:41], v[122:123]
	s_nop 1
	v_mfma_f32_16x16x32_bf16 v[38:41], v[128:131], v[50:53], v[38:41]
	ds_read_b128 v[120:123], v181 offset:57024
	ds_read_b64_tr_b16 v[128:129], v180 offset:27744
	ds_read_b64_tr_b16 v[130:131], v180 offset:32864
	s_waitcnt lgkmcnt(6)
	v_pk_mul_f32 v[34:35], v[34:35], v[124:125]
	v_pk_mul_f32 v[36:37], v[36:37], v[126:127]
	s_nop 1
	v_mfma_f32_16x16x32_bf16 v[34:37], v[132:135], v[50:53], v[34:37]
	ds_read_b128 v[124:127], v181 offset:57088
	ds_read_b64_tr_b16 v[132:133], v180 offset:27776
	ds_read_b64_tr_b16 v[134:135], v180 offset:32896
	s_waitcnt lgkmcnt(6)
	v_pk_mul_f32 v[30:31], v[30:31], v[144:145]
	v_pk_mul_f32 v[32:33], v[32:33], v[146:147]
	s_nop 1
	v_mfma_f32_16x16x32_bf16 v[30:33], v[136:139], v[50:53], v[30:33]
	ds_read_b128 v[144:147], v181 offset:57152
	ds_read_b64_tr_b16 v[136:137], v180 offset:27808
	ds_read_b64_tr_b16 v[138:139], v180 offset:32928
	s_waitcnt lgkmcnt(6)
	v_pk_mul_f32 v[26:27], v[26:27], v[120:121]
	v_pk_mul_f32 v[28:29], v[28:29], v[122:123]
	s_nop 1
	v_mfma_f32_16x16x32_bf16 v[26:29], v[128:131], v[50:53], v[26:29]
	ds_read_b128 v[120:123], v181 offset:57216
	ds_read_b64_tr_b16 v[128:129], v180 offset:27840
	ds_read_b64_tr_b16 v[130:131], v180 offset:32960
	s_waitcnt lgkmcnt(6)
	v_pk_mul_f32 v[22:23], v[22:23], v[124:125]
	v_pk_mul_f32 v[24:25], v[24:25], v[126:127]
	s_nop 1
	v_mfma_f32_16x16x32_bf16 v[22:25], v[132:135], v[50:53], v[22:25]
	ds_read_b128 v[124:127], v181 offset:57280
	ds_read_b64_tr_b16 v[132:133], v180 offset:27872
	ds_read_b64_tr_b16 v[134:135], v180 offset:32992
	s_waitcnt lgkmcnt(6)
	v_pk_mul_f32 v[18:19], v[18:19], v[144:145]
	v_pk_mul_f32 v[20:21], v[20:21], v[146:147]
	s_nop 1
	v_mfma_f32_16x16x32_bf16 v[18:21], v[136:139], v[50:53], v[18:21]
	s_waitcnt lgkmcnt(3)
	v_pk_mul_f32 v[12:13], v[12:13], v[120:121]
	v_pk_mul_f32 v[14:15], v[14:15], v[122:123]
	s_nop 1
	v_mfma_f32_16x16x32_bf16 v[12:15], v[128:131], v[50:53], v[12:15]
	s_waitcnt lgkmcnt(0)
	v_pk_mul_f32 v[8:9], v[8:9], v[124:125]
	v_pk_mul_f32 v[10:11], v[10:11], v[126:127]
	s_nop 1
	v_mfma_f32_16x16x32_bf16 v[8:11], v[132:135], v[50:53], v[8:11]
	s_cmp_ge_u32 s5, 4
	s_cbranch_scc1 .Lp1n_P
.Lp1n_R:
	s_cmp_gt_u32 s6, 5
	s_cbranch_scc1 .Lp1n_bar
	s_bitcmp1_b32 s6, 0
	s_cbranch_scc1 .Lp1n_odd
	s_waitcnt vmcnt(3)
	ds_write_b128 v188, v[46:49]
	s_waitcnt vmcnt(2)
	ds_write_b128 v187, v[42:45] offset:17408
	s_cmp_gt_u32 s6, 3
	s_cbranch_scc1 .Lp1n_bar
	s_mul_i32 s0, s6, 0x2c000
	s_add_u32 s0, s0, 0x6bb0000
	v_add_co_u32_e64 v42, s[0:1], s0, v62
	s_nop 1
	v_addc_co_u32_e64 v43, s[0:1], 0, v63, s[0:1]
	global_load_dwordx4 v[46:49], v[42:43], off offset:3584
	global_load_dwordx4 v[42:45], v[42:43], off offset:2560
	s_branch .Lp1n_bar
.Lp1n_odd:
	s_cmp_eq_u32 s6, 5
	s_cbranch_scc1 .Lp1n_odd5
	s_waitcnt vmcnt(3)
	ds_write_b128 v188, v[200:203]
	s_waitcnt vmcnt(2)
	ds_write_b128 v187, v[196:199] offset:17408
	s_cmp_gt_u32 s6, 3
	s_cbranch_scc1 .Lp1n_bar
	s_mul_i32 s0, s6, 0x2c000
	s_add_u32 s0, s0, 0x6bb0000
	v_add_co_u32_e64 v196, s[0:1], s0, v62
	s_nop 1
	v_addc_co_u32_e64 v197, s[0:1], 0, v63, s[0:1]
	global_load_dwordx4 v[200:203], v[196:197], off offset:3584
	global_load_dwordx4 v[196:199], v[196:197], off offset:2560
	s_branch .Lp1n_bar
.Lp1n_odd5:
	s_waitcnt vmcnt(1)
	ds_write_b128 v188, v[200:203]
	s_waitcnt vmcnt(0)
	ds_write_b128 v187, v[196:199] offset:17408
.Lp1n_bar:
	s_waitcnt lgkmcnt(0)
	s_barrier
	s_add_i32 s6, s6, 1
	s_cmp_lt_u32 s6, 7
	s_cbranch_scc1 .Lp1n_loop
	s_mov_b32 s7, 0xe400
	v_add_u32_e32 v180, s7, v71
	v_add_u32_e32 v181, s7, v68
	v_add_u32_e32 v183, s7, v73
	ds_read_b64_tr_b16 v[50:51], v183
	ds_read_b64_tr_b16 v[52:53], v183 offset:5120
	ds_read_b128 v[120:123], v181 offset:56832
	ds_read_b64_tr_b16 v[128:129], v180 offset:27648
	ds_read_b64_tr_b16 v[130:131], v180 offset:32768
	ds_read_b128 v[124:127], v181 offset:56896
	ds_read_b64_tr_b16 v[132:133], v180 offset:27680
	ds_read_b64_tr_b16 v[134:135], v180 offset:32800
	ds_read_b128 v[144:147], v181 offset:56960
	ds_read_b64_tr_b16 v[136:137], v180 offset:27712
	ds_read_b64_tr_b16 v[138:139], v180 offset:32832
	s_waitcnt lgkmcnt(6)
	v_pk_mul_f32 v[38:39], v[38:39], v[120:121]
	v_pk_mul_f32 v[40:41], v[40:41], v[122:123]
	s_nop 1
	v_mfma_f32_16x16x32_bf16 v[38:41], v[128:131], v[50:53], v[38:41]
	ds_read_b128 v[120:123], v181 offset:57024
	ds_read_b64_tr_b16 v[128:129], v180 offset:27744
	ds_read_b64_tr_b16 v[130:131], v180 offset:32864
	s_waitcnt lgkmcnt(6)
	v_pk_mul_f32 v[34:35], v[34:35], v[124:125]
	v_pk_mul_f32 v[36:37], v[36:37], v[126:127]
	s_nop 1
	v_mfma_f32_16x16x32_bf16 v[34:37], v[132:135], v[50:53], v[34:37]
	ds_read_b128 v[124:127], v181 offset:57088
	ds_read_b64_tr_b16 v[132:133], v180 offset:27776
	ds_read_b64_tr_b16 v[134:135], v180 offset:32896
	s_waitcnt lgkmcnt(6)
	v_pk_mul_f32 v[30:31], v[30:31], v[144:145]
	v_pk_mul_f32 v[32:33], v[32:33], v[146:147]
	s_nop 1
	v_mfma_f32_16x16x32_bf16 v[30:33], v[136:139], v[50:53], v[30:33]
	ds_read_b128 v[144:147], v181 offset:57152
	ds_read_b64_tr_b16 v[136:137], v180 offset:27808
	ds_read_b64_tr_b16 v[138:139], v180 offset:32928
	s_waitcnt lgkmcnt(6)
	v_pk_mul_f32 v[26:27], v[26:27], v[120:121]
	v_pk_mul_f32 v[28:29], v[28:29], v[122:123]
	s_nop 1
	v_mfma_f32_16x16x32_bf16 v[26:29], v[128:131], v[50:53], v[26:29]
	ds_read_b128 v[120:123], v181 offset:57216
	ds_read_b64_tr_b16 v[128:129], v180 offset:27840
	ds_read_b64_tr_b16 v[130:131], v180 offset:32960
	s_waitcnt lgkmcnt(6)
	v_pk_mul_f32 v[22:23], v[22:23], v[124:125]
	v_pk_mul_f32 v[24:25], v[24:25], v[126:127]
	s_nop 1
	v_mfma_f32_16x16x32_bf16 v[22:25], v[132:135], v[50:53], v[22:25]
	ds_read_b128 v[124:127], v181 offset:57280
	ds_read_b64_tr_b16 v[132:133], v180 offset:27872
	ds_read_b64_tr_b16 v[134:135], v180 offset:32992
	s_waitcnt lgkmcnt(6)
	v_pk_mul_f32 v[18:19], v[18:19], v[144:145]
	v_pk_mul_f32 v[20:21], v[20:21], v[146:147]
	s_nop 1
	v_mfma_f32_16x16x32_bf16 v[18:21], v[136:139], v[50:53], v[18:21]
	s_waitcnt lgkmcnt(3)
	v_pk_mul_f32 v[12:13], v[12:13], v[120:121]
	v_pk_mul_f32 v[14:15], v[14:15], v[122:123]
	s_nop 1
	v_mfma_f32_16x16x32_bf16 v[12:15], v[128:131], v[50:53], v[12:15]
	s_waitcnt lgkmcnt(0)
	v_pk_mul_f32 v[8:9], v[8:9], v[124:125]
	v_pk_mul_f32 v[10:11], v[10:11], v[126:127]
	s_nop 1
	v_mfma_f32_16x16x32_bf16 v[8:11], v[132:135], v[50:53], v[8:11]
	s_ashr_i32 s3, s2, 31
	s_lshl_b64 s[0:1], s[2:3], 15
	s_add_u32 s0, s62, s0
	s_addc_u32 s1, s63, s1
	v_lshl_or_b32 v96, s5, 11, v57
	v_ashrrev_i32_e32 v97, 31, v96
	s_lshl_b64 s[6:7], s[2:3], 9
	v_lshl_add_u64 v[96:97], v[96:97], 1, s[0:1]
	s_nop 7
	v_cvt_pk_bf16_f32 v38, v38, v39
	v_cvt_pk_bf16_f32 v39, v40, v41
	global_store_dwordx2 v[96:97], v[38:39], off
	v_cvt_pk_bf16_f32 v34, v34, v35
	v_cvt_pk_bf16_f32 v35, v36, v37
	global_store_dwordx2 v[96:97], v[34:35], off offset:512
	v_cvt_pk_bf16_f32 v30, v30, v31
	v_cvt_pk_bf16_f32 v31, v32, v33
	global_store_dwordx2 v[96:97], v[30:31], off offset:1024
	v_cvt_pk_bf16_f32 v26, v26, v27
	v_cvt_pk_bf16_f32 v27, v28, v29
	global_store_dwordx2 v[96:97], v[26:27], off offset:1536
	v_cvt_pk_bf16_f32 v22, v22, v23
	v_cvt_pk_bf16_f32 v23, v24, v25
	global_store_dwordx2 v[96:97], v[22:23], off offset:2048
	v_cvt_pk_bf16_f32 v18, v18, v19
	v_cvt_pk_bf16_f32 v19, v20, v21
	global_store_dwordx2 v[96:97], v[18:19], off offset:2560
	v_cvt_pk_bf16_f32 v12, v12, v13
	v_cvt_pk_bf16_f32 v13, v14, v15
	global_store_dwordx2 v[96:97], v[12:13], off offset:3072
	v_cvt_pk_bf16_f32 v8, v8, v9
	v_cvt_pk_bf16_f32 v9, v10, v11
	global_store_dwordx2 v[96:97], v[8:9], off offset:3584
	s_add_u32 s3, s64, s6
	s_addc_u32 s6, s65, s7
	s_ashr_i32 s5, s4, 31
	s_lshl_b64 s[4:5], s[4:5], 2
	s_add_u32 s4, s3, s4
	s_addc_u32 s5, s6, s5
	v_exp_f32_e32 v208, v208
	v_exp_f32_e32 v209, v209
	v_exp_f32_e32 v210, v210
	v_exp_f32_e32 v211, v211
	v_cmp_eq_u32_e64 s[6:7], 15, v56
	s_and_saveexec_b64 s[0:1], s[6:7]
	global_store_dwordx4 v68, v[208:211], s[4:5]
	s_branch .LBB0_1149
